# hyena Toeplitz loops: waves 4-7 start each MFMA loop ~256 cycles after waves 0-3 (wave-half stagger)
# speedup vs baseline: 1.0013x; 1.0013x over previous
.LBB0_483:
	v_mov_b32_e32 v6, 0
	v_mov_b32_e32 v12, 0
	v_mov_b32_e32 v13, 0
	v_mov_b32_e32 v14, 0
	v_mov_b32_e32 v15, 0
	ds_write_b128 v160, v[8:11]
	s_waitcnt lgkmcnt(0)
	s_barrier
	s_and_saveexec_b64 s[60:61], s[4:5]
	ds_read_b128 v[12:15], v160 offset:16
	s_or_b64 exec, exec, s[60:61]
	v_perm_b32 v17, v9, v10, s65
	v_perm_b32 v18, v10, v11, s65
	s_waitcnt lgkmcnt(0)
	v_perm_b32 v19, v11, v12, s65
	v_perm_b32 v16, v8, v9, s65
	v_pk_mov_b32 v[20:21], v[8:9], v[10:11] op_sel:[1,0]
	v_pk_mov_b32 v[22:23], v[10:11], v[12:13] op_sel:[1,0]
	v_perm_b32 v27, v12, v13, s65
	v_mov_b32_e32 v24, v17
	v_mov_b32_e32 v25, v18
	v_mov_b32_e32 v26, v19
	ds_write_b128 v160, v[16:19] offset:8224
	ds_write_b128 v160, v[20:23] offset:16448
	ds_write_b128 v160, v[24:27] offset:24672
	ds_write_b128 v160, v[10:13] offset:32896
	v_perm_b32 v11, v13, v14, s65
	v_mov_b32_e32 v8, v18
	v_mov_b32_e32 v9, v19
	v_mov_b32_e32 v10, v27
	v_pk_mov_b32 v[24:25], v[12:13], v[14:15] op_sel:[1,0]
	v_perm_b32 v15, v14, v15, s65
	v_mov_b32_e32 v12, v19
	v_mov_b32_e32 v13, v27
	v_mov_b32_e32 v14, v11
	ds_write_b128 v160, v[8:11] offset:41120
	ds_write_b128 v160, v[22:25] offset:49344
	ds_write_b128 v160, v[12:15] offset:57568
	s_waitcnt lgkmcnt(0)
	s_barrier
	v_readfirstlane_b32 s98, v193
	s_nop 0
	s_bitcmp1_b32 s98, 8
	s_cbranch_scc0 .Lhst_1
	s_sleep 4
.Lhst_1:
	ds_read_b128 v[70:73], v161 offset:4096
	ds_read_b128 v[66:69], v161 offset:4064
	ds_read_b128 v[78:81], v161 offset:4032
	ds_read_b128 v[74:77], v161 offset:4000
	ds_read_b128 v[86:89], v161 offset:3968
	ds_read_b128 v[82:85], v161 offset:3936
	ds_read_b128 v[94:97], v161 offset:3904
	ds_read_b128 v[90:93], v161 offset:3872
	ds_read_b128 v[102:105], v161 offset:3840
	ds_read_b128 v[98:101], v161 offset:3808
	ds_read_b128 v[110:113], v161 offset:3776
	ds_read_b128 v[106:109], v161 offset:3744
	ds_read_b128 v[118:121], v161 offset:3712
	ds_read_b128 v[114:117], v161 offset:3680
	ds_read_b128 v[122:125], v161 offset:3616
	ds_read_b128 v[126:129], v161 offset:3648
	v_add_u32_e32 v1, v153, v152
	ds_read_b128 v[134:137], v1
	s_mov_b32 s2, 0
	v_mov_b32_e32 v7, v6
	v_mov_b32_e32 v8, v6
	v_mov_b32_e32 v9, v6
	v_mov_b32_e32 v10, v6
	v_mov_b32_e32 v11, v6
	v_mov_b32_e32 v12, v6
	v_mov_b32_e32 v13, v6
	v_mov_b32_e32 v14, v6
	v_mov_b32_e32 v15, v6
	v_mov_b32_e32 v16, v6
	v_mov_b32_e32 v17, v6
	v_mov_b32_e32 v18, v6
	v_mov_b32_e32 v19, v6
	v_mov_b32_e32 v20, v6
	v_mov_b32_e32 v21, v6
	v_mov_b32_e32 v22, v6
	v_mov_b32_e32 v23, v6
	v_mov_b32_e32 v24, v6
	v_mov_b32_e32 v25, v6
	v_mov_b32_e32 v26, v6
	v_mov_b32_e32 v27, v6
	v_mov_b32_e32 v28, v6
	v_mov_b32_e32 v29, v6
	v_mov_b32_e32 v30, v6
	v_mov_b32_e32 v31, v6
	v_mov_b32_e32 v32, v6
	v_mov_b32_e32 v33, v6
	v_mov_b32_e32 v34, v6
	v_mov_b32_e32 v35, v6
	v_mov_b32_e32 v36, v6
	v_mov_b32_e32 v37, v6
	v_mov_b32_e32 v38, v6
	v_mov_b32_e32 v39, v6
	v_mov_b32_e32 v40, v6
	v_mov_b32_e32 v41, v6
	v_mov_b32_e32 v42, v6
	v_mov_b32_e32 v43, v6
	v_mov_b32_e32 v44, v6
	v_mov_b32_e32 v45, v6
	v_mov_b32_e32 v46, v6
	v_mov_b32_e32 v47, v6
	v_mov_b32_e32 v48, v6
	v_mov_b32_e32 v49, v6
	v_mov_b32_e32 v50, v6
	v_mov_b32_e32 v51, v6
	v_mov_b32_e32 v52, v6
	v_mov_b32_e32 v53, v6
	v_mov_b32_e32 v54, v6
	v_mov_b32_e32 v55, v6
	v_mov_b32_e32 v56, v6
	v_mov_b32_e32 v57, v6
	v_mov_b32_e32 v58, v6
	v_mov_b32_e32 v59, v6
	v_mov_b32_e32 v60, v6
	v_mov_b32_e32 v61, v6
	v_mov_b32_e32 v62, v6
	v_mov_b32_e32 v63, v6
	v_mov_b32_e32 v64, v6
	v_mov_b32_e32 v65, v6
	v_mov_b32_e32 v130, v6
	v_mov_b32_e32 v131, v6
	v_mov_b32_e32 v132, v6
	v_mov_b32_e32 v133, v6
.LBB0_486:
	v_add_u32_e32 v0, s2, v154
	v_add_u32_e32 v165, s2, v155
	s_waitcnt lgkmcnt(0)
	v_mfma_f32_16x16x32_bf16 v[10:13], v[126:129], v[134:137], v[10:13]
	v_add_u32_e32 v166, 0x10140, v165
	v_mfma_f32_16x16x32_bf16 v[6:9], v[122:125], v[134:137], v[6:9]
	ds_read_b128 v[122:125], v0
	ds_read_b128 v[126:129], v0 offset:32
	ds_read_b128 v[166:169], v166
	v_mfma_f32_16x16x32_bf16 v[130:133], v[70:73], v[134:137], v[130:133]
	v_mfma_f32_16x16x32_bf16 v[62:65], v[66:69], v[134:137], v[62:65]
	v_mfma_f32_16x16x32_bf16 v[58:61], v[78:81], v[134:137], v[58:61]
	v_mfma_f32_16x16x32_bf16 v[54:57], v[74:77], v[134:137], v[54:57]
	v_mfma_f32_16x16x32_bf16 v[50:53], v[86:89], v[134:137], v[50:53]
	v_mfma_f32_16x16x32_bf16 v[46:49], v[82:85], v[134:137], v[46:49]
	v_mfma_f32_16x16x32_bf16 v[42:45], v[94:97], v[134:137], v[42:45]
	v_mfma_f32_16x16x32_bf16 v[38:41], v[90:93], v[134:137], v[38:41]
	v_mfma_f32_16x16x32_bf16 v[34:37], v[102:105], v[134:137], v[34:37]
	v_mfma_f32_16x16x32_bf16 v[30:33], v[98:101], v[134:137], v[30:33]
	v_mfma_f32_16x16x32_bf16 v[26:29], v[110:113], v[134:137], v[26:29]
	v_mfma_f32_16x16x32_bf16 v[22:25], v[106:109], v[134:137], v[22:25]
	v_mfma_f32_16x16x32_bf16 v[18:21], v[118:121], v[134:137], v[18:21]
	v_mfma_f32_16x16x32_bf16 v[14:17], v[114:117], v[134:137], v[14:17]
	v_add_u32_e32 v134, 0x10180, v165
	s_waitcnt lgkmcnt(0)
	v_mfma_f32_16x16x32_bf16 v[10:13], v[118:121], v[166:169], v[10:13]
	v_mfma_f32_16x16x32_bf16 v[6:9], v[114:117], v[166:169], v[6:9]
	ds_read_b128 v[114:117], v0 offset:64
	ds_read_b128 v[118:121], v0 offset:96
	ds_read_b128 v[134:137], v134
	v_mfma_f32_16x16x32_bf16 v[130:133], v[126:129], v[166:169], v[130:133]
	v_mfma_f32_16x16x32_bf16 v[62:65], v[122:125], v[166:169], v[62:65]
	v_mfma_f32_16x16x32_bf16 v[58:61], v[70:73], v[166:169], v[58:61]
	v_mfma_f32_16x16x32_bf16 v[54:57], v[66:69], v[166:169], v[54:57]
	v_mfma_f32_16x16x32_bf16 v[50:53], v[78:81], v[166:169], v[50:53]
	v_mfma_f32_16x16x32_bf16 v[46:49], v[74:77], v[166:169], v[46:49]
	v_mfma_f32_16x16x32_bf16 v[42:45], v[86:89], v[166:169], v[42:45]
	v_mfma_f32_16x16x32_bf16 v[38:41], v[82:85], v[166:169], v[38:41]
	v_mfma_f32_16x16x32_bf16 v[34:37], v[94:97], v[166:169], v[34:37]
	v_mfma_f32_16x16x32_bf16 v[30:33], v[90:93], v[166:169], v[30:33]
	v_mfma_f32_16x16x32_bf16 v[26:29], v[102:105], v[166:169], v[26:29]
	v_mfma_f32_16x16x32_bf16 v[22:25], v[98:101], v[166:169], v[22:25]
	v_mfma_f32_16x16x32_bf16 v[18:21], v[110:113], v[166:169], v[18:21]
	v_mfma_f32_16x16x32_bf16 v[14:17], v[106:109], v[166:169], v[14:17]
	s_waitcnt lgkmcnt(0)
	v_mfma_f32_16x16x32_bf16 v[10:13], v[110:113], v[134:137], v[10:13]
	v_add_u32_e32 v166, 0x101c0, v165
	v_mfma_f32_16x16x32_bf16 v[6:9], v[106:109], v[134:137], v[6:9]
	ds_read_b128 v[106:109], v0 offset:128
	ds_read_b128 v[110:113], v0 offset:160
	ds_read_b128 v[166:169], v166
	v_mfma_f32_16x16x32_bf16 v[130:133], v[118:121], v[134:137], v[130:133]
	v_mfma_f32_16x16x32_bf16 v[62:65], v[114:117], v[134:137], v[62:65]
	v_mfma_f32_16x16x32_bf16 v[58:61], v[126:129], v[134:137], v[58:61]
	v_mfma_f32_16x16x32_bf16 v[54:57], v[122:125], v[134:137], v[54:57]
	v_mfma_f32_16x16x32_bf16 v[50:53], v[70:73], v[134:137], v[50:53]
	v_mfma_f32_16x16x32_bf16 v[46:49], v[66:69], v[134:137], v[46:49]
	v_mfma_f32_16x16x32_bf16 v[42:45], v[78:81], v[134:137], v[42:45]
	v_mfma_f32_16x16x32_bf16 v[38:41], v[74:77], v[134:137], v[38:41]
	v_mfma_f32_16x16x32_bf16 v[34:37], v[86:89], v[134:137], v[34:37]
	v_mfma_f32_16x16x32_bf16 v[30:33], v[82:85], v[134:137], v[30:33]
	v_mfma_f32_16x16x32_bf16 v[26:29], v[94:97], v[134:137], v[26:29]
	v_mfma_f32_16x16x32_bf16 v[22:25], v[90:93], v[134:137], v[22:25]
	v_mfma_f32_16x16x32_bf16 v[18:21], v[102:105], v[134:137], v[18:21]
	v_mfma_f32_16x16x32_bf16 v[14:17], v[98:101], v[134:137], v[14:17]
	v_add_u32_e32 v134, 0x10200, v165
	s_waitcnt lgkmcnt(0)
	v_mfma_f32_16x16x32_bf16 v[10:13], v[102:105], v[166:169], v[10:13]
	v_mfma_f32_16x16x32_bf16 v[6:9], v[98:101], v[166:169], v[6:9]
	ds_read_b128 v[98:101], v0 offset:192
	ds_read_b128 v[102:105], v0 offset:224
	ds_read_b128 v[134:137], v134
	v_mfma_f32_16x16x32_bf16 v[130:133], v[110:113], v[166:169], v[130:133]
	v_mfma_f32_16x16x32_bf16 v[62:65], v[106:109], v[166:169], v[62:65]
	v_mfma_f32_16x16x32_bf16 v[58:61], v[118:121], v[166:169], v[58:61]
	v_mfma_f32_16x16x32_bf16 v[54:57], v[114:117], v[166:169], v[54:57]
	v_mfma_f32_16x16x32_bf16 v[50:53], v[126:129], v[166:169], v[50:53]
	v_mfma_f32_16x16x32_bf16 v[46:49], v[122:125], v[166:169], v[46:49]
	v_mfma_f32_16x16x32_bf16 v[42:45], v[70:73], v[166:169], v[42:45]
	v_mfma_f32_16x16x32_bf16 v[38:41], v[66:69], v[166:169], v[38:41]
	v_mfma_f32_16x16x32_bf16 v[34:37], v[78:81], v[166:169], v[34:37]
	v_mfma_f32_16x16x32_bf16 v[30:33], v[74:77], v[166:169], v[30:33]
	v_mfma_f32_16x16x32_bf16 v[26:29], v[86:89], v[166:169], v[26:29]
	v_mfma_f32_16x16x32_bf16 v[22:25], v[82:85], v[166:169], v[22:25]
	v_mfma_f32_16x16x32_bf16 v[18:21], v[94:97], v[166:169], v[18:21]
	v_mfma_f32_16x16x32_bf16 v[14:17], v[90:93], v[166:169], v[14:17]
	s_waitcnt lgkmcnt(0)
	v_mfma_f32_16x16x32_bf16 v[10:13], v[94:97], v[134:137], v[10:13]
	v_add_u32_e32 v166, 0x10240, v165
	v_mfma_f32_16x16x32_bf16 v[6:9], v[90:93], v[134:137], v[6:9]
	ds_read_b128 v[90:93], v0 offset:256
	ds_read_b128 v[94:97], v0 offset:288
	ds_read_b128 v[166:169], v166
	v_mfma_f32_16x16x32_bf16 v[130:133], v[102:105], v[134:137], v[130:133]
	v_mfma_f32_16x16x32_bf16 v[62:65], v[98:101], v[134:137], v[62:65]
	v_mfma_f32_16x16x32_bf16 v[58:61], v[110:113], v[134:137], v[58:61]
	v_mfma_f32_16x16x32_bf16 v[54:57], v[106:109], v[134:137], v[54:57]
	v_mfma_f32_16x16x32_bf16 v[50:53], v[118:121], v[134:137], v[50:53]
	v_mfma_f32_16x16x32_bf16 v[46:49], v[114:117], v[134:137], v[46:49]
	v_mfma_f32_16x16x32_bf16 v[42:45], v[126:129], v[134:137], v[42:45]
	v_mfma_f32_16x16x32_bf16 v[38:41], v[122:125], v[134:137], v[38:41]
	v_mfma_f32_16x16x32_bf16 v[34:37], v[70:73], v[134:137], v[34:37]
	v_mfma_f32_16x16x32_bf16 v[30:33], v[66:69], v[134:137], v[30:33]
	v_mfma_f32_16x16x32_bf16 v[26:29], v[78:81], v[134:137], v[26:29]
	v_mfma_f32_16x16x32_bf16 v[22:25], v[74:77], v[134:137], v[22:25]
	v_mfma_f32_16x16x32_bf16 v[18:21], v[86:89], v[134:137], v[18:21]
	v_mfma_f32_16x16x32_bf16 v[14:17], v[82:85], v[134:137], v[14:17]
	v_add_u32_e32 v134, 0x10280, v165
	s_waitcnt lgkmcnt(0)
	v_mfma_f32_16x16x32_bf16 v[10:13], v[86:89], v[166:169], v[10:13]
	v_mfma_f32_16x16x32_bf16 v[6:9], v[82:85], v[166:169], v[6:9]
	ds_read_b128 v[82:85], v0 offset:320
	ds_read_b128 v[86:89], v0 offset:352
	ds_read_b128 v[134:137], v134
	v_mfma_f32_16x16x32_bf16 v[130:133], v[94:97], v[166:169], v[130:133]
	v_mfma_f32_16x16x32_bf16 v[62:65], v[90:93], v[166:169], v[62:65]
	v_mfma_f32_16x16x32_bf16 v[58:61], v[102:105], v[166:169], v[58:61]
	v_mfma_f32_16x16x32_bf16 v[54:57], v[98:101], v[166:169], v[54:57]
	v_mfma_f32_16x16x32_bf16 v[50:53], v[110:113], v[166:169], v[50:53]
	v_mfma_f32_16x16x32_bf16 v[46:49], v[106:109], v[166:169], v[46:49]
	v_mfma_f32_16x16x32_bf16 v[42:45], v[118:121], v[166:169], v[42:45]
	v_mfma_f32_16x16x32_bf16 v[38:41], v[114:117], v[166:169], v[38:41]
	v_mfma_f32_16x16x32_bf16 v[34:37], v[126:129], v[166:169], v[34:37]
	v_mfma_f32_16x16x32_bf16 v[30:33], v[122:125], v[166:169], v[30:33]
	v_mfma_f32_16x16x32_bf16 v[26:29], v[70:73], v[166:169], v[26:29]
	v_mfma_f32_16x16x32_bf16 v[22:25], v[66:69], v[166:169], v[22:25]
	v_mfma_f32_16x16x32_bf16 v[18:21], v[78:81], v[166:169], v[18:21]
	v_mfma_f32_16x16x32_bf16 v[14:17], v[74:77], v[166:169], v[14:17]
	s_waitcnt lgkmcnt(0)
	v_mfma_f32_16x16x32_bf16 v[10:13], v[78:81], v[134:137], v[10:13]
	v_add_u32_e32 v166, 0x102c0, v165
	v_mfma_f32_16x16x32_bf16 v[6:9], v[74:77], v[134:137], v[6:9]
	ds_read_b128 v[74:77], v0 offset:384
	ds_read_b128 v[78:81], v0 offset:416
	ds_read_b128 v[166:169], v166
	v_mfma_f32_16x16x32_bf16 v[130:133], v[86:89], v[134:137], v[130:133]
	v_mfma_f32_16x16x32_bf16 v[62:65], v[82:85], v[134:137], v[62:65]
	v_mfma_f32_16x16x32_bf16 v[58:61], v[94:97], v[134:137], v[58:61]
	v_mfma_f32_16x16x32_bf16 v[54:57], v[90:93], v[134:137], v[54:57]
	v_mfma_f32_16x16x32_bf16 v[50:53], v[102:105], v[134:137], v[50:53]
	v_mfma_f32_16x16x32_bf16 v[46:49], v[98:101], v[134:137], v[46:49]
	v_mfma_f32_16x16x32_bf16 v[42:45], v[110:113], v[134:137], v[42:45]
	v_mfma_f32_16x16x32_bf16 v[38:41], v[106:109], v[134:137], v[38:41]
	v_mfma_f32_16x16x32_bf16 v[34:37], v[118:121], v[134:137], v[34:37]
	v_mfma_f32_16x16x32_bf16 v[30:33], v[114:117], v[134:137], v[30:33]
	v_mfma_f32_16x16x32_bf16 v[26:29], v[126:129], v[134:137], v[26:29]
	v_mfma_f32_16x16x32_bf16 v[22:25], v[122:125], v[134:137], v[22:25]
	v_mfma_f32_16x16x32_bf16 v[18:21], v[70:73], v[134:137], v[18:21]
	v_mfma_f32_16x16x32_bf16 v[14:17], v[66:69], v[134:137], v[14:17]
	s_waitcnt lgkmcnt(0)
	v_mfma_f32_16x16x32_bf16 v[10:13], v[70:73], v[166:169], v[10:13]
	v_mfma_f32_16x16x32_bf16 v[6:9], v[66:69], v[166:169], v[6:9]
	ds_read_b128 v[66:69], v0 offset:448
	ds_read_b128 v[70:73], v0 offset:480
	v_add_u32_e32 v0, 0x10300, v165
	ds_read_b128 v[134:137], v0
	v_mfma_f32_16x16x32_bf16 v[130:133], v[78:81], v[166:169], v[130:133]
	v_mfma_f32_16x16x32_bf16 v[62:65], v[74:77], v[166:169], v[62:65]
	v_mfma_f32_16x16x32_bf16 v[58:61], v[86:89], v[166:169], v[58:61]
	v_mfma_f32_16x16x32_bf16 v[54:57], v[82:85], v[166:169], v[54:57]
	v_mfma_f32_16x16x32_bf16 v[50:53], v[94:97], v[166:169], v[50:53]
	v_mfma_f32_16x16x32_bf16 v[46:49], v[90:93], v[166:169], v[46:49]
	v_mfma_f32_16x16x32_bf16 v[42:45], v[102:105], v[166:169], v[42:45]
	v_mfma_f32_16x16x32_bf16 v[38:41], v[98:101], v[166:169], v[38:41]
	v_mfma_f32_16x16x32_bf16 v[34:37], v[110:113], v[166:169], v[34:37]
	v_mfma_f32_16x16x32_bf16 v[30:33], v[106:109], v[166:169], v[30:33]
	v_mfma_f32_16x16x32_bf16 v[26:29], v[118:121], v[166:169], v[26:29]
	v_mfma_f32_16x16x32_bf16 v[22:25], v[114:117], v[166:169], v[22:25]
	v_mfma_f32_16x16x32_bf16 v[18:21], v[126:129], v[166:169], v[18:21]
	v_mfma_f32_16x16x32_bf16 v[14:17], v[122:125], v[166:169], v[14:17]
	s_addk_i32 s2, 0x200
	s_cmpk_lg_i32 s2, 0x1000
	s_cbranch_scc1 .LBB0_486
	s_add_u32 s2, s74, s58
	s_addc_u32 s3, s75, s59
	v_mov_b32_e32 v0, 0
	s_waitcnt lgkmcnt(2)
	global_load_dword v66, v0, s[2:3]
	s_waitcnt lgkmcnt(0)
	global_load_dword v134, v0, s[2:3] offset:2048
	global_load_dword v72, v0, s[44:45] offset:2048
	global_load_dword v74, v0, s[48:49] offset:2048
	global_load_dword v70, v158, s[44:45]
	global_load_dword v68, v157, s[44:45] offset:2048
	s_lshl_b64 s[2:3], s[50:51], 16
	v_lshl_add_u64 v[82:83], v[144:145], 0, s[2:3]
	flat_load_dwordx2 v[84:85], v[82:83]
	flat_load_dwordx2 v[136:137], v[82:83] offset:32
	flat_load_dwordx2 v[128:129], v[82:83] offset:64
	flat_load_dwordx2 v[124:125], v[82:83] offset:96
	flat_load_dwordx2 v[120:121], v[82:83] offset:128
	flat_load_dwordx2 v[116:117], v[82:83] offset:160
	flat_load_dwordx2 v[112:113], v[82:83] offset:192
	flat_load_dwordx2 v[108:109], v[82:83] offset:224
	flat_load_dwordx2 v[104:105], v[82:83] offset:256
	flat_load_dwordx2 v[100:101], v[82:83] offset:288
	flat_load_dwordx2 v[94:95], v[82:83] offset:320
	flat_load_dwordx2 v[90:91], v[82:83] offset:352
	v_lshl_add_u64 v[76:77], v[146:147], 1, v[82:83]
	flat_load_ushort v67, v[76:77]
	flat_load_dwordx2 v[86:87], v[82:83] offset:384
	flat_load_dwordx2 v[80:81], v[82:83] offset:416
	flat_load_dwordx2 v[78:79], v[82:83] offset:448
	s_nop 0
	flat_load_dwordx2 v[76:77], v[82:83] offset:480
	v_lshl_add_u64 v[82:83], v[82:83], 0, v[140:141]
	flat_load_ushort v89, v[82:83] offset:480
	s_waitcnt vmcnt(0) lgkmcnt(0)
	ds_bpermute_b32 v69, v162, v85
	v_cndmask_b32_e64 v71, v84, v136, s[12:13]
	v_cndmask_b32_e64 v73, v137, v85, s[10:11]
	v_cndmask_b32_e64 v82, v129, v137, s[10:11]
	v_cndmask_b32_e64 v92, v124, v120, s[12:13]
	s_waitcnt lgkmcnt(0)
	v_lshrrev_b32_e32 v69, 16, v69
	v_cndmask_b32_e64 v99, v113, v117, s[10:11]
	v_cndmask_b32_e64 v102, v112, v108, s[12:13]
	v_cndmask_b32_e64 v93, v121, v125, s[10:11]
	v_cndmask_b32_e64 v111, v101, v105, s[10:11]
	v_cndmask_b32_e64 v115, v95, v101, s[10:11]
	v_cndmask_b32_e64 v119, v91, v95, s[10:11]
	v_cndmask_b32_e64 v67, v67, 0, s[8:9]
	v_cndmask_b32_e64 v96, v120, v116, s[12:13]
	v_cndmask_b32_e64 v103, v109, v113, s[10:11]
	ds_bpermute_b32 v165, v163, v92
	ds_bpermute_b32 v92, v162, v99
	ds_bpermute_b32 v99, v163, v102
	ds_bpermute_b32 v102, v162, v111
	ds_bpermute_b32 v111, v162, v115
	ds_bpermute_b32 v115, v162, v119
	v_cndmask_b32_e64 v119, v69, v67, s[12:13]
	v_cndmask_b32_e64 v67, v87, v91, s[10:11]
	ds_bpermute_b32 v123, v163, v71
	ds_bpermute_b32 v71, v162, v73
	ds_bpermute_b32 v73, v162, v82
	ds_bpermute_b32 v82, v162, v93
	ds_bpermute_b32 v93, v163, v96
	ds_bpermute_b32 v96, v162, v103
	ds_bpermute_b32 v67, v162, v67
	v_cndmask_b32_e64 v75, v136, v128, s[12:13]
	v_cndmask_b32_e64 v88, v125, v129, s[10:11]
	v_cndmask_b32_e64 v114, v100, v94, s[12:13]
	ds_bpermute_b32 v127, v163, v75
	ds_bpermute_b32 v75, v162, v88
	ds_bpermute_b32 v186, v163, v114
	s_waitcnt lgkmcnt(8)
	v_and_b32_e32 v170, 0xffff0000, v71
	s_waitcnt lgkmcnt(4)
	v_and_b32_e32 v114, 0xffff0000, v96
	v_cndmask_b32_e64 v71, v81, v87, s[10:11]
	s_waitcnt lgkmcnt(3)
	v_and_b32_e32 v96, 0xffff0000, v67
	v_cndmask_b32_e64 v67, v86, v80, s[12:13]
	v_cndmask_b32_e64 v97, v117, v121, s[10:11]
	v_and_b32_e32 v172, 0xffff0000, v73
	ds_bpermute_b32 v71, v162, v71
	ds_bpermute_b32 v73, v163, v67
	v_cndmask_b32_e64 v67, v79, v81, s[10:11]
	ds_bpermute_b32 v88, v162, v97
	ds_bpermute_b32 v67, v162, v67
	v_cndmask_b32_e64 v69, v90, v86, s[12:13]
	v_cndmask_b32_e64 v83, v128, v124, s[12:13]
	v_cndmask_b32_e64 v118, v94, v90, s[12:13]
	s_waitcnt lgkmcnt(5)
	v_and_b32_e32 v174, 0xffff0000, v75
	ds_bpermute_b32 v75, v163, v69
	v_cndmask_b32_e64 v69, v80, v78, s[12:13]
	ds_bpermute_b32 v135, v163, v83
	ds_bpermute_b32 v83, v163, v118
	v_and_b32_e32 v118, 0xffff0000, v92
	s_waitcnt lgkmcnt(6)
	v_and_b32_e32 v92, 0xffff0000, v71
	ds_bpermute_b32 v71, v163, v69
	v_and_b32_e32 v167, 0xffff0000, v85
	s_waitcnt lgkmcnt(5)
	v_and_b32_e32 v122, 0xffff0000, v88
	v_cndmask_b32_e64 v69, v77, v79, s[10:11]
	s_waitcnt lgkmcnt(4)
	v_and_b32_e32 v88, 0xffff0000, v67
	ds_bpermute_b32 v67, v163, v76
	v_lshlrev_b32_e32 v178, 16, v85
	v_and_b32_e32 v166, 16, v85
	v_mov_b32_e32 v179, v167
	v_and_b32_e32 v126, 0xffff0000, v82
	ds_bpermute_b32 v82, v162, v69
	v_cndmask_b32_e64 v69, v78, v76, s[12:13]
	v_pk_mov_b32 v[180:181], v[166:167], v[178:179] op_sel:[1,0]
	ds_bpermute_b32 v69, v163, v69
	v_and_b32_e32 v176, 0xffff0000, v84
	v_mov_b32_e32 v177, v181
	s_waitcnt lgkmcnt(6)
	v_pk_fma_f32 v[166:167], v[72:73], v[176:177], v[74:75] op_sel_hi:[0,1,0]
	v_cndmask_b32_e64 v89, v89, 0, s[14:15]
	s_waitcnt lgkmcnt(3)
	v_pk_fma_f32 v[182:183], v[70:71], v[178:179], v[166:167] op_sel_hi:[0,1,1]
	ds_read2_b64 v[166:169], v164 offset1:4
	s_waitcnt lgkmcnt(3)
	v_cndmask_b32_e64 v67, v67, v89, s[10:11]
	v_lshlrev_b32_e32 v89, 16, v123
	v_mov_b32_e32 v181, v89
	s_waitcnt lgkmcnt(1)
	v_pk_fma_f32 v[180:181], v[68:69], v[180:181], v[182:183] op_sel_hi:[0,1,1]
	v_lshlrev_b32_e32 v182, 16, v119
	v_lshlrev_b32_e32 v183, 16, v84
	v_pk_fma_f32 v[84:85], v[72:73], v[182:183], v[74:75] op_sel_hi:[0,1,0]
	v_pk_mov_b32 v[182:183], v[182:183], v[176:177] op_sel:[1,0]
	s_waitcnt lgkmcnt(0)
	v_lshlrev_b32_e32 v184, 16, v166
	v_and_b32_e32 v185, 0xffff0000, v166
	v_pk_fma_f32 v[84:85], v[70:71], v[182:183], v[84:85] op_sel_hi:[0,1,1]
	v_mov_b32_e32 v177, v178
	v_pk_fma_f32 v[130:131], v[66:67], v[184:185], v[130:131] op_sel_hi:[0,1,1]
	v_pk_fma_f32 v[84:85], v[68:69], v[176:177], v[84:85] op_sel_hi:[0,1,1]
	v_pk_mul_f32 v[84:85], v[84:85], v[130:131]
	v_lshlrev_b32_e32 v130, 16, v167
	v_and_b32_e32 v131, 0xffff0000, v167
	v_pk_fma_f32 v[130:131], v[66:67], v[130:131], v[132:133] op_sel_hi:[0,1,1]
	v_and_b32_e32 v167, 0xffff0000, v137
	v_pk_mul_f32 v[130:131], v[180:181], v[130:131]
	v_lshlrev_b32_e32 v132, 16, v137
	v_and_b32_e32 v166, 16, v137
	v_mov_b32_e32 v133, v167
	v_cvt_pk_bf16_f32 v84, v84, v85
	v_cvt_pk_bf16_f32 v85, v130, v131
	v_lshlrev_b32_e32 v171, 16, v136
	v_and_b32_e32 v130, 0xffff0000, v136
	v_pk_mov_b32 v[136:137], v[166:167], v[132:133] op_sel:[1,0]
	v_lshlrev_b32_e32 v89, 16, v127
	v_mov_b32_e32 v131, v137
	v_pk_fma_f32 v[166:167], v[72:73], v[130:131], v[74:75] op_sel_hi:[0,1,0]
	v_mov_b32_e32 v137, v89
	v_pk_fma_f32 v[166:167], v[70:71], v[132:133], v[166:167] op_sel_hi:[0,1,1]
	v_pk_fma_f32 v[136:137], v[68:69], v[136:137], v[166:167] op_sel_hi:[0,1,1]
	v_pk_fma_f32 v[166:167], v[72:73], v[170:171], v[74:75] op_sel_hi:[0,1,0]
	v_pk_mov_b32 v[170:171], v[170:171], v[130:131] op_sel:[1,0]
	v_lshlrev_b32_e32 v176, 16, v168
	v_and_b32_e32 v177, 0xffff0000, v168
	v_pk_fma_f32 v[166:167], v[70:71], v[170:171], v[166:167] op_sel_hi:[0,1,1]
	v_mov_b32_e32 v131, v132
	v_pk_fma_f32 v[62:63], v[66:67], v[176:177], v[62:63] op_sel_hi:[0,1,1]
	v_pk_fma_f32 v[130:131], v[68:69], v[130:131], v[166:167] op_sel_hi:[0,1,1]
	v_pk_mul_f32 v[62:63], v[130:131], v[62:63]
	v_lshlrev_b32_e32 v130, 16, v169
	v_and_b32_e32 v131, 0xffff0000, v169
	v_pk_fma_f32 v[64:65], v[66:67], v[130:131], v[64:65] op_sel_hi:[0,1,1]
	v_pk_mul_f32 v[64:65], v[136:137], v[64:65]
	ds_read2_b64 v[130:133], v164 offset0:8 offset1:12
	v_and_b32_e32 v137, 0xffff0000, v129
	v_cvt_pk_bf16_f32 v62, v62, v63
	v_cvt_pk_bf16_f32 v63, v64, v65
	v_lshlrev_b32_e32 v173, 16, v128
	v_and_b32_e32 v64, 0xffff0000, v128
	v_lshlrev_b32_e32 v128, 16, v129
	v_and_b32_e32 v136, 16, v129
	v_mov_b32_e32 v129, v137
	v_pk_mov_b32 v[136:137], v[136:137], v[128:129] op_sel:[1,0]
	v_lshlrev_b32_e32 v89, 16, v135
	v_mov_b32_e32 v65, v137
	v_pk_fma_f32 v[166:167], v[72:73], v[64:65], v[74:75] op_sel_hi:[0,1,0]
	v_mov_b32_e32 v137, v89
	v_pk_fma_f32 v[166:167], v[70:71], v[128:129], v[166:167] op_sel_hi:[0,1,1]
	s_waitcnt lgkmcnt(0)
	v_lshlrev_b32_e32 v168, 16, v130
	v_and_b32_e32 v169, 0xffff0000, v130
	v_pk_fma_f32 v[136:137], v[68:69], v[136:137], v[166:167] op_sel_hi:[0,1,1]
	v_pk_fma_f32 v[166:167], v[72:73], v[172:173], v[74:75] op_sel_hi:[0,1,0]
	v_pk_fma_f32 v[58:59], v[66:67], v[168:169], v[58:59] op_sel_hi:[0,1,1]
	v_pk_mov_b32 v[168:169], v[172:173], v[64:65] op_sel:[1,0]
	v_mov_b32_e32 v65, v128
	v_pk_fma_f32 v[166:167], v[70:71], v[168:169], v[166:167] op_sel_hi:[0,1,1]
	v_pk_fma_f32 v[64:65], v[68:69], v[64:65], v[166:167] op_sel_hi:[0,1,1]
	v_pk_mul_f32 v[58:59], v[64:65], v[58:59]
	v_lshlrev_b32_e32 v64, 16, v131
	v_and_b32_e32 v65, 0xffff0000, v131
	v_pk_fma_f32 v[60:61], v[66:67], v[64:65], v[60:61] op_sel_hi:[0,1,1]
	v_and_b32_e32 v129, 0xffff0000, v125
	v_pk_mul_f32 v[60:61], v[136:137], v[60:61]
	v_lshlrev_b32_e32 v64, 16, v125
	v_and_b32_e32 v128, 16, v125
	v_mov_b32_e32 v65, v129
	v_cvt_pk_bf16_f32 v58, v58, v59
	v_cvt_pk_bf16_f32 v59, v60, v61
	v_lshlrev_b32_e32 v175, 16, v124
	v_and_b32_e32 v60, 0xffff0000, v124
	v_pk_mov_b32 v[124:125], v[128:129], v[64:65] op_sel:[1,0]
	v_lshlrev_b32_e32 v89, 16, v165
	v_mov_b32_e32 v61, v125
	v_pk_fma_f32 v[128:129], v[72:73], v[60:61], v[74:75] op_sel_hi:[0,1,0]
	v_mov_b32_e32 v125, v89
	v_pk_fma_f32 v[128:129], v[70:71], v[64:65], v[128:129] op_sel_hi:[0,1,1]
	v_lshlrev_b32_e32 v130, 16, v132
	v_and_b32_e32 v131, 0xffff0000, v132
	v_pk_fma_f32 v[124:125], v[68:69], v[124:125], v[128:129] op_sel_hi:[0,1,1]
	v_pk_fma_f32 v[128:129], v[72:73], v[174:175], v[74:75] op_sel_hi:[0,1,0]
	v_pk_fma_f32 v[54:55], v[66:67], v[130:131], v[54:55] op_sel_hi:[0,1,1]
	v_pk_mov_b32 v[130:131], v[174:175], v[60:61] op_sel:[1,0]
	v_mov_b32_e32 v61, v64
	v_pk_fma_f32 v[128:129], v[70:71], v[130:131], v[128:129] op_sel_hi:[0,1,1]
	v_pk_fma_f32 v[60:61], v[68:69], v[60:61], v[128:129] op_sel_hi:[0,1,1]
	v_pk_mul_f32 v[54:55], v[60:61], v[54:55]
	v_lshlrev_b32_e32 v60, 16, v133
	v_and_b32_e32 v61, 0xffff0000, v133
	ds_read2_b64 v[128:131], v164 offset0:16 offset1:20
	v_and_b32_e32 v65, 0xffff0000, v121
	v_pk_fma_f32 v[56:57], v[66:67], v[60:61], v[56:57] op_sel_hi:[0,1,1]
	v_lshlrev_b32_e32 v60, 16, v121
	v_and_b32_e32 v64, 16, v121
	v_mov_b32_e32 v61, v65
	v_pk_mul_f32 v[56:57], v[124:125], v[56:57]
	v_pk_mov_b32 v[64:65], v[64:65], v[60:61] op_sel:[1,0]
	v_cvt_pk_bf16_f32 v54, v54, v55
	v_cvt_pk_bf16_f32 v55, v56, v57
	v_and_b32_e32 v56, 0xffff0000, v120
	v_mov_b32_e32 v57, v65
	v_lshlrev_b32_e32 v89, 16, v93
	v_lshlrev_b32_e32 v127, 16, v120
	v_pk_fma_f32 v[120:121], v[72:73], v[56:57], v[74:75] op_sel_hi:[0,1,0]
	v_mov_b32_e32 v65, v89
	v_pk_fma_f32 v[120:121], v[70:71], v[60:61], v[120:121] op_sel_hi:[0,1,1]
	s_waitcnt lgkmcnt(0)
	v_lshlrev_b32_e32 v124, 16, v128
	v_and_b32_e32 v125, 0xffff0000, v128
	v_cndmask_b32_e64 v98, v116, v112, s[12:13]
	v_pk_fma_f32 v[64:65], v[68:69], v[64:65], v[120:121] op_sel_hi:[0,1,1]
	v_pk_fma_f32 v[120:121], v[72:73], v[126:127], v[74:75] op_sel_hi:[0,1,0]
	v_pk_fma_f32 v[50:51], v[66:67], v[124:125], v[50:51] op_sel_hi:[0,1,1]
	v_pk_mov_b32 v[124:125], v[126:127], v[56:57] op_sel:[1,0]
	ds_bpermute_b32 v97, v163, v98
	v_pk_fma_f32 v[120:121], v[70:71], v[124:125], v[120:121] op_sel_hi:[0,1,1]
	v_mov_b32_e32 v57, v60
	v_pk_fma_f32 v[56:57], v[68:69], v[56:57], v[120:121] op_sel_hi:[0,1,1]
	v_pk_mul_f32 v[50:51], v[56:57], v[50:51]
	v_lshlrev_b32_e32 v56, 16, v129
	v_and_b32_e32 v57, 0xffff0000, v129
	v_and_b32_e32 v61, 0xffff0000, v117
	v_pk_fma_f32 v[52:53], v[66:67], v[56:57], v[52:53] op_sel_hi:[0,1,1]
	v_lshlrev_b32_e32 v56, 16, v117
	v_and_b32_e32 v60, 16, v117
	v_mov_b32_e32 v57, v61
	v_pk_mul_f32 v[52:53], v[64:65], v[52:53]
	v_pk_mov_b32 v[60:61], v[60:61], v[56:57] op_sel:[1,0]
	v_cvt_pk_bf16_f32 v50, v50, v51
	v_cvt_pk_bf16_f32 v51, v52, v53
	s_waitcnt lgkmcnt(0)
	v_lshlrev_b32_e32 v64, 16, v97
	v_and_b32_e32 v52, 0xffff0000, v116
	v_mov_b32_e32 v53, v61
	v_mov_b32_e32 v61, v64
	v_pk_fma_f32 v[64:65], v[72:73], v[52:53], v[74:75] op_sel_hi:[0,1,0]
	v_lshlrev_b32_e32 v123, 16, v116
	v_pk_fma_f32 v[64:65], v[70:71], v[56:57], v[64:65] op_sel_hi:[0,1,1]
	v_lshlrev_b32_e32 v116, 16, v130
	v_and_b32_e32 v117, 0xffff0000, v130
	v_pk_fma_f32 v[60:61], v[68:69], v[60:61], v[64:65] op_sel_hi:[0,1,1]
	v_pk_fma_f32 v[64:65], v[72:73], v[122:123], v[74:75] op_sel_hi:[0,1,0]
	v_pk_fma_f32 v[46:47], v[66:67], v[116:117], v[46:47] op_sel_hi:[0,1,1]
	v_pk_mov_b32 v[116:117], v[122:123], v[52:53] op_sel:[1,0]
	v_mov_b32_e32 v53, v56
	v_pk_fma_f32 v[64:65], v[70:71], v[116:117], v[64:65] op_sel_hi:[0,1,1]
	v_pk_fma_f32 v[52:53], v[68:69], v[52:53], v[64:65] op_sel_hi:[0,1,1]
	v_pk_mul_f32 v[46:47], v[52:53], v[46:47]
	v_lshlrev_b32_e32 v52, 16, v131
	v_and_b32_e32 v53, 0xffff0000, v131
	ds_read2_b64 v[120:123], v164 offset0:24 offset1:28
	v_and_b32_e32 v57, 0xffff0000, v113
	v_pk_fma_f32 v[48:49], v[66:67], v[52:53], v[48:49] op_sel_hi:[0,1,1]
	v_lshlrev_b32_e32 v52, 16, v113
	v_and_b32_e32 v56, 16, v113
	v_mov_b32_e32 v53, v57
	v_pk_mul_f32 v[48:49], v[60:61], v[48:49]
	v_pk_mov_b32 v[56:57], v[56:57], v[52:53] op_sel:[1,0]
	v_cvt_pk_bf16_f32 v46, v46, v47
	v_cvt_pk_bf16_f32 v47, v48, v49
	v_lshlrev_b32_e32 v60, 16, v99
	v_and_b32_e32 v48, 0xffff0000, v112
	v_mov_b32_e32 v49, v57
	v_mov_b32_e32 v57, v60
	v_pk_fma_f32 v[60:61], v[72:73], v[48:49], v[74:75] op_sel_hi:[0,1,0]
	v_lshlrev_b32_e32 v119, 16, v112
	v_pk_fma_f32 v[60:61], v[70:71], v[52:53], v[60:61] op_sel_hi:[0,1,1]
	s_waitcnt lgkmcnt(0)
	v_lshlrev_b32_e32 v64, 16, v120
	v_and_b32_e32 v65, 0xffff0000, v120
	v_cndmask_b32_e64 v106, v108, v104, s[12:13]
	v_pk_fma_f32 v[56:57], v[68:69], v[56:57], v[60:61] op_sel_hi:[0,1,1]
	v_pk_fma_f32 v[60:61], v[72:73], v[118:119], v[74:75] op_sel_hi:[0,1,0]
	v_pk_fma_f32 v[42:43], v[66:67], v[64:65], v[42:43] op_sel_hi:[0,1,1]
	v_pk_mov_b32 v[64:65], v[118:119], v[48:49] op_sel:[1,0]
	ds_bpermute_b32 v103, v163, v106
	v_pk_fma_f32 v[60:61], v[70:71], v[64:65], v[60:61] op_sel_hi:[0,1,1]
	v_mov_b32_e32 v49, v52
	v_cndmask_b32_e64 v107, v105, v109, s[10:11]
	v_pk_fma_f32 v[48:49], v[68:69], v[48:49], v[60:61] op_sel_hi:[0,1,1]
	ds_bpermute_b32 v98, v162, v107
	v_pk_mul_f32 v[42:43], v[48:49], v[42:43]
	v_lshlrev_b32_e32 v48, 16, v121
	v_and_b32_e32 v49, 0xffff0000, v121
	v_and_b32_e32 v53, 0xffff0000, v109
	v_pk_fma_f32 v[44:45], v[66:67], v[48:49], v[44:45] op_sel_hi:[0,1,1]
	v_lshlrev_b32_e32 v48, 16, v109
	v_and_b32_e32 v52, 16, v109
	v_mov_b32_e32 v49, v53
	v_pk_mul_f32 v[44:45], v[56:57], v[44:45]
	v_pk_mov_b32 v[52:53], v[52:53], v[48:49] op_sel:[1,0]
	v_cvt_pk_bf16_f32 v42, v42, v43
	v_cvt_pk_bf16_f32 v43, v44, v45
	s_waitcnt lgkmcnt(1)
	v_lshlrev_b32_e32 v56, 16, v103
	v_and_b32_e32 v44, 0xffff0000, v108
	v_mov_b32_e32 v45, v53
	v_cndmask_b32_e64 v110, v104, v100, s[12:13]
	v_mov_b32_e32 v53, v56
	v_pk_fma_f32 v[56:57], v[72:73], v[44:45], v[74:75] op_sel_hi:[0,1,0]
	ds_bpermute_b32 v107, v163, v110
	s_waitcnt lgkmcnt(1)
	v_and_b32_e32 v110, 0xffff0000, v98
	v_and_b32_e32 v98, 0xffff0000, v115
	v_lshlrev_b32_e32 v115, 16, v108
	v_pk_fma_f32 v[56:57], v[70:71], v[48:49], v[56:57] op_sel_hi:[0,1,1]
	v_lshlrev_b32_e32 v60, 16, v122
	v_and_b32_e32 v61, 0xffff0000, v122
	v_pk_fma_f32 v[52:53], v[68:69], v[52:53], v[56:57] op_sel_hi:[0,1,1]
	v_pk_fma_f32 v[56:57], v[72:73], v[114:115], v[74:75] op_sel_hi:[0,1,0]
	v_pk_fma_f32 v[38:39], v[66:67], v[60:61], v[38:39] op_sel_hi:[0,1,1]
	v_pk_mov_b32 v[60:61], v[114:115], v[44:45] op_sel:[1,0]
	v_mov_b32_e32 v45, v48
	v_pk_fma_f32 v[56:57], v[70:71], v[60:61], v[56:57] op_sel_hi:[0,1,1]
	v_pk_fma_f32 v[44:45], v[68:69], v[44:45], v[56:57] op_sel_hi:[0,1,1]
	v_pk_mul_f32 v[38:39], v[44:45], v[38:39]
	v_lshlrev_b32_e32 v44, 16, v123
	v_and_b32_e32 v45, 0xffff0000, v123
	ds_read2_b64 v[112:115], v164 offset0:32 offset1:36
	v_and_b32_e32 v49, 0xffff0000, v105
	v_pk_fma_f32 v[40:41], v[66:67], v[44:45], v[40:41] op_sel_hi:[0,1,1]
	v_lshlrev_b32_e32 v44, 16, v105
	v_and_b32_e32 v48, 16, v105
	v_mov_b32_e32 v45, v49
	v_pk_mul_f32 v[40:41], v[52:53], v[40:41]
	v_pk_mov_b32 v[48:49], v[48:49], v[44:45] op_sel:[1,0]
	v_cvt_pk_bf16_f32 v38, v38, v39
	v_cvt_pk_bf16_f32 v39, v40, v41
	s_waitcnt lgkmcnt(1)
	v_lshlrev_b32_e32 v52, 16, v107
	v_and_b32_e32 v40, 0xffff0000, v104
	v_mov_b32_e32 v41, v49
	v_mov_b32_e32 v49, v52
	v_pk_fma_f32 v[52:53], v[72:73], v[40:41], v[74:75] op_sel_hi:[0,1,0]
	v_and_b32_e32 v106, 0xffff0000, v102
	v_and_b32_e32 v102, 0xffff0000, v111
	v_lshlrev_b32_e32 v111, 16, v104
	v_pk_fma_f32 v[52:53], v[70:71], v[44:45], v[52:53] op_sel_hi:[0,1,1]
	s_waitcnt lgkmcnt(0)
	v_lshlrev_b32_e32 v56, 16, v112
	v_and_b32_e32 v57, 0xffff0000, v112
	v_pk_fma_f32 v[48:49], v[68:69], v[48:49], v[52:53] op_sel_hi:[0,1,1]
	v_pk_fma_f32 v[52:53], v[72:73], v[110:111], v[74:75] op_sel_hi:[0,1,0]
	v_pk_fma_f32 v[34:35], v[66:67], v[56:57], v[34:35] op_sel_hi:[0,1,1]
	v_pk_mov_b32 v[56:57], v[110:111], v[40:41] op_sel:[1,0]
	v_mov_b32_e32 v41, v44
	v_pk_fma_f32 v[52:53], v[70:71], v[56:57], v[52:53] op_sel_hi:[0,1,1]
	v_pk_fma_f32 v[40:41], v[68:69], v[40:41], v[52:53] op_sel_hi:[0,1,1]
	v_pk_mul_f32 v[34:35], v[40:41], v[34:35]
	v_lshlrev_b32_e32 v40, 16, v113
	v_and_b32_e32 v41, 0xffff0000, v113
	v_and_b32_e32 v45, 0xffff0000, v101
	v_pk_fma_f32 v[36:37], v[66:67], v[40:41], v[36:37] op_sel_hi:[0,1,1]
	v_lshlrev_b32_e32 v40, 16, v101
	v_and_b32_e32 v44, 16, v101
	v_mov_b32_e32 v41, v45
	v_pk_mul_f32 v[36:37], v[48:49], v[36:37]
	v_pk_mov_b32 v[44:45], v[44:45], v[40:41] op_sel:[1,0]
	v_cvt_pk_bf16_f32 v34, v34, v35
	v_cvt_pk_bf16_f32 v35, v36, v37
	v_lshlrev_b32_e32 v48, 16, v186
	v_and_b32_e32 v36, 0xffff0000, v100
	v_mov_b32_e32 v37, v45
	v_mov_b32_e32 v45, v48
	v_pk_fma_f32 v[48:49], v[72:73], v[36:37], v[74:75] op_sel_hi:[0,1,0]
	v_lshlrev_b32_e32 v107, 16, v100
	v_pk_fma_f32 v[48:49], v[70:71], v[40:41], v[48:49] op_sel_hi:[0,1,1]
	v_lshlrev_b32_e32 v52, 16, v114
	v_and_b32_e32 v53, 0xffff0000, v114
	v_pk_fma_f32 v[44:45], v[68:69], v[44:45], v[48:49] op_sel_hi:[0,1,1]
	v_pk_fma_f32 v[48:49], v[72:73], v[106:107], v[74:75] op_sel_hi:[0,1,0]
	v_pk_fma_f32 v[30:31], v[66:67], v[52:53], v[30:31] op_sel_hi:[0,1,1]
	v_pk_mov_b32 v[52:53], v[106:107], v[36:37] op_sel:[1,0]
	v_mov_b32_e32 v37, v40
	v_pk_fma_f32 v[48:49], v[70:71], v[52:53], v[48:49] op_sel_hi:[0,1,1]
	v_pk_fma_f32 v[36:37], v[68:69], v[36:37], v[48:49] op_sel_hi:[0,1,1]
	v_pk_mul_f32 v[30:31], v[36:37], v[30:31]
	v_lshlrev_b32_e32 v36, 16, v115
	v_and_b32_e32 v37, 0xffff0000, v115
	ds_read2_b64 v[104:107], v164 offset0:40 offset1:44
	v_and_b32_e32 v41, 0xffff0000, v95
	v_pk_fma_f32 v[32:33], v[66:67], v[36:37], v[32:33] op_sel_hi:[0,1,1]
	v_lshlrev_b32_e32 v36, 16, v95
	v_and_b32_e32 v40, 16, v95
	v_mov_b32_e32 v37, v41
	v_pk_mul_f32 v[32:33], v[44:45], v[32:33]
	v_pk_mov_b32 v[40:41], v[40:41], v[36:37] op_sel:[1,0]
	v_cvt_pk_bf16_f32 v30, v30, v31
	v_cvt_pk_bf16_f32 v31, v32, v33
	v_lshlrev_b32_e32 v44, 16, v83
	v_and_b32_e32 v32, 0xffff0000, v94
	v_mov_b32_e32 v33, v41
	v_mov_b32_e32 v41, v44
	v_pk_fma_f32 v[44:45], v[72:73], v[32:33], v[74:75] op_sel_hi:[0,1,0]
	v_lshlrev_b32_e32 v103, 16, v94
	v_pk_fma_f32 v[44:45], v[70:71], v[36:37], v[44:45] op_sel_hi:[0,1,1]
	s_waitcnt lgkmcnt(0)
	v_lshlrev_b32_e32 v48, 16, v104
	v_and_b32_e32 v49, 0xffff0000, v104
	v_pk_fma_f32 v[40:41], v[68:69], v[40:41], v[44:45] op_sel_hi:[0,1,1]
	v_pk_fma_f32 v[44:45], v[72:73], v[102:103], v[74:75] op_sel_hi:[0,1,0]
	v_pk_fma_f32 v[26:27], v[66:67], v[48:49], v[26:27] op_sel_hi:[0,1,1]
	v_pk_mov_b32 v[48:49], v[102:103], v[32:33] op_sel:[1,0]
	v_mov_b32_e32 v33, v36
	v_pk_fma_f32 v[44:45], v[70:71], v[48:49], v[44:45] op_sel_hi:[0,1,1]
	v_pk_fma_f32 v[32:33], v[68:69], v[32:33], v[44:45] op_sel_hi:[0,1,1]
	v_pk_mul_f32 v[26:27], v[32:33], v[26:27]
	v_lshlrev_b32_e32 v32, 16, v105
	v_and_b32_e32 v33, 0xffff0000, v105
	v_and_b32_e32 v37, 0xffff0000, v91
	v_pk_fma_f32 v[28:29], v[66:67], v[32:33], v[28:29] op_sel_hi:[0,1,1]
	v_lshlrev_b32_e32 v32, 16, v91
	v_and_b32_e32 v36, 16, v91
	v_mov_b32_e32 v33, v37
	v_pk_mul_f32 v[28:29], v[40:41], v[28:29]
	v_pk_mov_b32 v[36:37], v[36:37], v[32:33] op_sel:[1,0]
	v_cvt_pk_bf16_f32 v26, v26, v27
	v_cvt_pk_bf16_f32 v27, v28, v29
	v_lshlrev_b32_e32 v40, 16, v75
	v_and_b32_e32 v28, 0xffff0000, v90
	v_mov_b32_e32 v29, v37
	v_mov_b32_e32 v37, v40
	v_pk_fma_f32 v[40:41], v[72:73], v[28:29], v[74:75] op_sel_hi:[0,1,0]
	v_lshlrev_b32_e32 v99, 16, v90
	v_pk_fma_f32 v[40:41], v[70:71], v[32:33], v[40:41] op_sel_hi:[0,1,1]
	v_lshlrev_b32_e32 v44, 16, v106
	v_and_b32_e32 v45, 0xffff0000, v106
	v_pk_fma_f32 v[36:37], v[68:69], v[36:37], v[40:41] op_sel_hi:[0,1,1]
	v_pk_fma_f32 v[40:41], v[72:73], v[98:99], v[74:75] op_sel_hi:[0,1,0]
	v_pk_fma_f32 v[22:23], v[66:67], v[44:45], v[22:23] op_sel_hi:[0,1,1]
	v_pk_mov_b32 v[44:45], v[98:99], v[28:29] op_sel:[1,0]
	v_mov_b32_e32 v29, v32
	v_pk_fma_f32 v[40:41], v[70:71], v[44:45], v[40:41] op_sel_hi:[0,1,1]
	v_pk_fma_f32 v[28:29], v[68:69], v[28:29], v[40:41] op_sel_hi:[0,1,1]
	v_pk_mul_f32 v[22:23], v[28:29], v[22:23]
	v_and_b32_e32 v41, 0xffff0000, v87
	v_cvt_pk_bf16_f32 v28, v22, v23
	v_lshlrev_b32_e32 v22, 16, v107
	v_and_b32_e32 v23, 0xffff0000, v107
	v_pk_fma_f32 v[22:23], v[66:67], v[22:23], v[24:25] op_sel_hi:[0,1,1]
	v_pk_mul_f32 v[22:23], v[36:37], v[22:23]
	v_lshlrev_b32_e32 v36, 16, v87
	v_cvt_pk_bf16_f32 v29, v22, v23
	ds_read2_b64 v[22:25], v164 offset0:48 offset1:52
	v_and_b32_e32 v40, 16, v87
	v_mov_b32_e32 v37, v41
	v_pk_mov_b32 v[40:41], v[40:41], v[36:37] op_sel:[1,0]
	v_lshlrev_b32_e32 v44, 16, v73
	v_and_b32_e32 v32, 0xffff0000, v86
	v_mov_b32_e32 v33, v41
	v_mov_b32_e32 v41, v44
	v_pk_fma_f32 v[44:45], v[72:73], v[32:33], v[74:75] op_sel_hi:[0,1,0]
	v_lshlrev_b32_e32 v97, 16, v86
	v_pk_fma_f32 v[44:45], v[70:71], v[36:37], v[44:45] op_sel_hi:[0,1,1]
	s_waitcnt lgkmcnt(0)
	v_lshlrev_b32_e32 v48, 16, v22
	v_and_b32_e32 v49, 0xffff0000, v22
	v_pk_fma_f32 v[40:41], v[68:69], v[40:41], v[44:45] op_sel_hi:[0,1,1]
	v_pk_fma_f32 v[44:45], v[72:73], v[96:97], v[74:75] op_sel_hi:[0,1,0]
	v_pk_fma_f32 v[18:19], v[66:67], v[48:49], v[18:19] op_sel_hi:[0,1,1]
	v_pk_mov_b32 v[48:49], v[96:97], v[32:33] op_sel:[1,0]
	v_mov_b32_e32 v33, v36
	v_pk_fma_f32 v[44:45], v[70:71], v[48:49], v[44:45] op_sel_hi:[0,1,1]
	v_pk_fma_f32 v[32:33], v[68:69], v[32:33], v[44:45] op_sel_hi:[0,1,1]
	v_pk_mul_f32 v[18:19], v[32:33], v[18:19]
	v_lshlrev_b32_e32 v22, 16, v23
	v_and_b32_e32 v23, 0xffff0000, v23
	v_and_b32_e32 v33, 0xffff0000, v81
	v_pk_fma_f32 v[20:21], v[66:67], v[22:23], v[20:21] op_sel_hi:[0,1,1]
	v_lshlrev_b32_e32 v22, 16, v81
	v_and_b32_e32 v32, 16, v81
	v_mov_b32_e32 v23, v33
	v_pk_mul_f32 v[20:21], v[40:41], v[20:21]
	v_pk_mov_b32 v[32:33], v[32:33], v[22:23] op_sel:[1,0]
	v_cvt_pk_bf16_f32 v18, v18, v19
	v_cvt_pk_bf16_f32 v19, v20, v21
	v_lshlrev_b32_e32 v36, 16, v71
	v_and_b32_e32 v20, 0xffff0000, v80
	v_mov_b32_e32 v21, v33
	v_mov_b32_e32 v33, v36
	v_pk_fma_f32 v[36:37], v[72:73], v[20:21], v[74:75] op_sel_hi:[0,1,0]
	v_lshlrev_b32_e32 v93, 16, v80
	v_pk_fma_f32 v[36:37], v[70:71], v[22:23], v[36:37] op_sel_hi:[0,1,1]
	v_lshlrev_b32_e32 v40, 16, v24
	v_and_b32_e32 v41, 0xffff0000, v24
	v_pk_fma_f32 v[32:33], v[68:69], v[32:33], v[36:37] op_sel_hi:[0,1,1]
	v_pk_fma_f32 v[36:37], v[72:73], v[92:93], v[74:75] op_sel_hi:[0,1,0]
	v_pk_fma_f32 v[14:15], v[66:67], v[40:41], v[14:15] op_sel_hi:[0,1,1]
	v_pk_mov_b32 v[40:41], v[92:93], v[20:21] op_sel:[1,0]
	v_mov_b32_e32 v21, v22
	v_pk_fma_f32 v[36:37], v[70:71], v[40:41], v[36:37] op_sel_hi:[0,1,1]
	v_pk_fma_f32 v[20:21], v[68:69], v[20:21], v[36:37] op_sel_hi:[0,1,1]
	v_pk_mul_f32 v[14:15], v[20:21], v[14:15]
	v_lshlrev_b32_e32 v24, 16, v79
	v_cvt_pk_bf16_f32 v20, v14, v15
	v_lshlrev_b32_e32 v14, 16, v25
	v_and_b32_e32 v15, 0xffff0000, v25
	v_pk_fma_f32 v[14:15], v[66:67], v[14:15], v[16:17] op_sel_hi:[0,1,1]
	v_pk_mul_f32 v[14:15], v[32:33], v[14:15]
	v_and_b32_e32 v33, 0xffff0000, v79
	v_cvt_pk_bf16_f32 v21, v14, v15
	ds_read2_b64 v[14:17], v164 offset0:56 offset1:60
	v_and_b32_e32 v32, 16, v79
	v_mov_b32_e32 v25, v33
	v_pk_mov_b32 v[32:33], v[32:33], v[24:25] op_sel:[1,0]
	v_lshlrev_b32_e32 v36, 16, v69
	v_and_b32_e32 v22, 0xffff0000, v78
	v_mov_b32_e32 v23, v33
	v_mov_b32_e32 v33, v36
	v_pk_fma_f32 v[36:37], v[72:73], v[22:23], v[74:75] op_sel_hi:[0,1,0]
	v_lshlrev_b32_e32 v89, 16, v78
	v_pk_fma_f32 v[36:37], v[70:71], v[24:25], v[36:37] op_sel_hi:[0,1,1]
	s_waitcnt lgkmcnt(0)
	v_lshlrev_b32_e32 v40, 16, v14
	v_and_b32_e32 v41, 0xffff0000, v14
	v_pk_fma_f32 v[32:33], v[68:69], v[32:33], v[36:37] op_sel_hi:[0,1,1]
	v_pk_fma_f32 v[36:37], v[72:73], v[88:89], v[74:75] op_sel_hi:[0,1,0]
	v_pk_fma_f32 v[10:11], v[66:67], v[40:41], v[10:11] op_sel_hi:[0,1,1]
	v_pk_mov_b32 v[40:41], v[88:89], v[22:23] op_sel:[1,0]
	v_mov_b32_e32 v23, v24
	v_pk_fma_f32 v[36:37], v[70:71], v[40:41], v[36:37] op_sel_hi:[0,1,1]
	v_pk_fma_f32 v[22:23], v[68:69], v[22:23], v[36:37] op_sel_hi:[0,1,1]
	v_pk_mul_f32 v[10:11], v[22:23], v[10:11]
	v_lshlrev_b32_e32 v14, 16, v15
	v_and_b32_e32 v15, 0xffff0000, v15
	v_and_b32_e32 v23, 0xffff0000, v77
	v_pk_fma_f32 v[12:13], v[66:67], v[14:15], v[12:13] op_sel_hi:[0,1,1]
	v_lshlrev_b32_e32 v14, 16, v77
	v_and_b32_e32 v22, 16, v77
	v_mov_b32_e32 v15, v23
	v_pk_mul_f32 v[12:13], v[32:33], v[12:13]
	v_pk_mov_b32 v[22:23], v[22:23], v[14:15] op_sel:[1,0]
	v_cvt_pk_bf16_f32 v10, v10, v11
	v_cvt_pk_bf16_f32 v11, v12, v13
	v_lshlrev_b32_e32 v24, 16, v67
	v_and_b32_e32 v12, 0xffff0000, v76
	v_mov_b32_e32 v13, v23
	v_mov_b32_e32 v23, v24
	v_pk_fma_f32 v[24:25], v[72:73], v[12:13], v[74:75] op_sel_hi:[0,1,0]
	v_and_b32_e32 v82, 0xffff0000, v82
	v_lshlrev_b32_e32 v83, 16, v76
	v_pk_fma_f32 v[24:25], v[70:71], v[14:15], v[24:25] op_sel_hi:[0,1,1]
	v_lshlrev_b32_e32 v32, 16, v16
	v_and_b32_e32 v33, 0xffff0000, v16
	v_pk_fma_f32 v[22:23], v[68:69], v[22:23], v[24:25] op_sel_hi:[0,1,1]
	v_pk_fma_f32 v[24:25], v[72:73], v[82:83], v[74:75] op_sel_hi:[0,1,0]
	v_pk_fma_f32 v[6:7], v[66:67], v[32:33], v[6:7] op_sel_hi:[0,1,1]
	v_pk_mov_b32 v[32:33], v[82:83], v[12:13] op_sel:[1,0]
	v_mov_b32_e32 v13, v14
	v_pk_fma_f32 v[24:25], v[70:71], v[32:33], v[24:25] op_sel_hi:[0,1,1]
	v_pk_fma_f32 v[12:13], v[68:69], v[12:13], v[24:25] op_sel_hi:[0,1,1]
	v_pk_mul_f32 v[6:7], v[12:13], v[6:7]
	v_lshlrev_b32_e32 v12, 16, v17
	v_and_b32_e32 v13, 0xffff0000, v17
	v_pk_fma_f32 v[8:9], v[66:67], v[12:13], v[8:9] op_sel_hi:[0,1,1]
	v_pk_mul_f32 v[8:9], v[22:23], v[8:9]
	v_cvt_pk_bf16_f32 v6, v6, v7
	v_cvt_pk_bf16_f32 v7, v8, v9
	s_barrier
	ds_write2_b64 v164, v[84:85], v[62:63] offset1:4
	ds_write2_b64 v164, v[58:59], v[54:55] offset0:8 offset1:12
	ds_write2_b64 v164, v[50:51], v[46:47] offset0:16 offset1:20
	ds_write2_b64 v164, v[42:43], v[38:39] offset0:24 offset1:28
	ds_write2_b64 v164, v[34:35], v[30:31] offset0:32 offset1:36
	ds_write2_b64 v164, v[26:27], v[28:29] offset0:40 offset1:44
	ds_write2_b64 v164, v[18:19], v[20:21] offset0:48 offset1:52
	ds_write2_b64 v164, v[10:11], v[6:7] offset0:56 offset1:60
	ds_write_b128 v160, v[2:5]
	v_mov_b32_e32 v6, 0
	v_mov_b32_e32 v7, 0
	v_mov_b32_e32 v8, 0
	v_mov_b32_e32 v9, 0
	s_waitcnt lgkmcnt(0)
	s_barrier
	s_and_saveexec_b64 s[50:51], s[4:5]
	ds_read_b128 v[6:9], v160 offset:16
	s_or_b64 exec, exec, s[50:51]
	v_perm_b32 v11, v3, v4, s65
	v_perm_b32 v12, v4, v5, s65
	s_waitcnt lgkmcnt(0)
	v_perm_b32 v13, v5, v6, s65
	v_perm_b32 v10, v2, v3, s65
	v_pk_mov_b32 v[14:15], v[2:3], v[4:5] op_sel:[1,0]
	v_pk_mov_b32 v[16:17], v[4:5], v[6:7] op_sel:[1,0]
	v_perm_b32 v21, v6, v7, s65
	v_mov_b32_e32 v18, v11
	v_mov_b32_e32 v19, v12
	v_mov_b32_e32 v20, v13
	ds_write_b128 v160, v[10:13] offset:8224
	ds_write_b128 v160, v[14:17] offset:16448
	ds_write_b128 v160, v[18:21] offset:24672
	ds_write_b128 v160, v[4:7] offset:32896
	v_perm_b32 v5, v7, v8, s65
	v_mov_b32_e32 v2, v12
	v_mov_b32_e32 v3, v13
	v_mov_b32_e32 v4, v21
	v_pk_mov_b32 v[18:19], v[6:7], v[8:9] op_sel:[1,0]
	v_perm_b32 v9, v8, v9, s65
	v_mov_b32_e32 v6, v13
	v_mov_b32_e32 v7, v21
	v_mov_b32_e32 v8, v5
	ds_write_b128 v160, v[2:5] offset:41120
	ds_write_b128 v160, v[16:19] offset:49344
	ds_write_b128 v160, v[6:9] offset:57568
	s_waitcnt lgkmcnt(0)
	s_barrier
	v_readfirstlane_b32 s98, v193
	s_nop 0
	s_bitcmp1_b32 s98, 8
	s_cbranch_scc0 .Lhst_0
	s_sleep 4
.Lhst_0:
	ds_read_b128 v[64:67], v161 offset:4096
	ds_read_b128 v[60:63], v161 offset:4064
	ds_read_b128 v[72:75], v161 offset:4032
	ds_read_b128 v[68:71], v161 offset:4000
	ds_read_b128 v[80:83], v161 offset:3968
	ds_read_b128 v[76:79], v161 offset:3936
	ds_read_b128 v[88:91], v161 offset:3904
	ds_read_b128 v[84:87], v161 offset:3872
	ds_read_b128 v[96:99], v161 offset:3840
	ds_read_b128 v[92:95], v161 offset:3808
	ds_read_b128 v[104:107], v161 offset:3776
	ds_read_b128 v[100:103], v161 offset:3744
	ds_read_b128 v[112:115], v161 offset:3712
	ds_read_b128 v[108:111], v161 offset:3680
	ds_read_b128 v[116:119], v161 offset:3616
	ds_read_b128 v[120:123], v161 offset:3648
	ds_read_b128 v[128:131], v1
	s_mov_b32 s2, 0
	v_mov_b32_e32 v1, v0
	v_mov_b32_e32 v2, v0
	v_mov_b32_e32 v3, v0
	v_mov_b32_e32 v4, v0
	v_mov_b32_e32 v5, v0
	v_mov_b32_e32 v6, v0
	v_mov_b32_e32 v7, v0
	v_mov_b32_e32 v8, v0
	v_mov_b32_e32 v9, v0
	v_mov_b32_e32 v10, v0
	v_mov_b32_e32 v11, v0
	v_mov_b32_e32 v12, v0
	v_mov_b32_e32 v13, v0
	v_mov_b32_e32 v14, v0
	v_mov_b32_e32 v15, v0
	v_mov_b32_e32 v16, v0
	v_mov_b32_e32 v17, v0
	v_mov_b32_e32 v18, v0
	v_mov_b32_e32 v19, v0
	v_mov_b32_e32 v20, v0
	v_mov_b32_e32 v21, v0
	v_mov_b32_e32 v22, v0
	v_mov_b32_e32 v23, v0
	v_mov_b32_e32 v24, v0
	v_mov_b32_e32 v25, v0
	v_mov_b32_e32 v26, v0
	v_mov_b32_e32 v27, v0
	v_mov_b32_e32 v28, v0
	v_mov_b32_e32 v29, v0
	v_mov_b32_e32 v30, v0
	v_mov_b32_e32 v31, v0
	v_mov_b32_e32 v32, v0
	v_mov_b32_e32 v33, v0
	v_mov_b32_e32 v34, v0
	v_mov_b32_e32 v35, v0
	v_mov_b32_e32 v36, v0
	v_mov_b32_e32 v37, v0
	v_mov_b32_e32 v38, v0
	v_mov_b32_e32 v39, v0
	v_mov_b32_e32 v40, v0
	v_mov_b32_e32 v41, v0
	v_mov_b32_e32 v42, v0
	v_mov_b32_e32 v43, v0
	v_mov_b32_e32 v44, v0
	v_mov_b32_e32 v45, v0
	v_mov_b32_e32 v46, v0
	v_mov_b32_e32 v47, v0
	v_mov_b32_e32 v48, v0
	v_mov_b32_e32 v49, v0
	v_mov_b32_e32 v50, v0
	v_mov_b32_e32 v51, v0
	v_mov_b32_e32 v52, v0
	v_mov_b32_e32 v53, v0
	v_mov_b32_e32 v54, v0
	v_mov_b32_e32 v55, v0
	v_mov_b32_e32 v56, v0
	v_mov_b32_e32 v57, v0
	v_mov_b32_e32 v58, v0
	v_mov_b32_e32 v59, v0
	v_mov_b32_e32 v124, v0
	v_mov_b32_e32 v125, v0
	v_mov_b32_e32 v126, v0
	v_mov_b32_e32 v127, v0
